# pooling phase rewritten by hand: two tokens per iteration sharing 17 h rows in registers, same summation order (on top of v94)
# baseline (speedup 1.0000x reference)
.LBB0_229:
	s_or_b64 exec, exec, s[2:3]
	s_cmp_lg_u32 s26, 3
	s_cselect_b64 s[0:1], -1, 0
	v_writelane_b32 v254, s0, 59
	s_cmp_eq_u32 s26, 3
	s_waitcnt lgkmcnt(0)
	v_writelane_b32 v254, s1, 60
	s_cselect_b64 s[0:1], -1, 0
	v_writelane_b32 v254, s0, 61
	s_barrier
	s_nop 0
	v_writelane_b32 v254, s1, 62
	s_and_b64 s[0:1], s[0:1], exec
	s_cselect_b32 s0, 0, s26
	s_cmp_lg_u32 s0, 0
	s_cselect_b64 s[2:3], -1, 0
	v_writelane_b32 v254, s2, 63
	s_and_b64 vcc, exec, s[2:3]
	s_nop 0
	v_writelane_b32 v255, s3, 0
	v_writelane_b32 v255, s26, 1
	v_writelane_b32 v255, s0, 2
	s_cbranch_vccz .LBB0_245
	s_cmp_lg_u32 s0, 1
	s_mov_b64 s[0:1], -1
	s_cbranch_scc0 .LBB0_288
	s_getreg_b32 s0, hwreg(HW_REG_HW_ID, 0, 6)
	s_and_b32 s0, s0, 63
	s_lshl_b32 s0, s0, 2
	s_add_i32 s0, s0, 0x22ef0
	v_mov_b32_e32 v0, s0
	ds_read_b32 v0, v0
	v_mbcnt_lo_u32_b32 v1, -1, v177
	v_mbcnt_hi_u32_b32 v1, -1, v1
	v_readlane_b32 s30, v254, 31
	v_readlane_b32 s31, v254, 32
	v_readlane_b32 s1, v253, 5
	v_lshlrev_b32_e32 v211, 5, v1
	v_lshrrev_b32_e32 v2, 4, v1
	v_lshlrev_b32_e64 v210, v2, 2
	s_waitcnt lgkmcnt(0)
	v_readfirstlane_b32 s0, v0
	s_nop 0
	s_add_i32 s1, s1, s0
	s_lshl_b32 s5, s1, 1
	s_add_u32 s44, s66, 0x6500000
	s_addc_u32 s45, s67, 0
	s_mov_b32 s1, 0
.Lpool_it:
	s_lshl_b32 s0, s1, 12
	s_add_i32 s0, s0, s5
	s_lshr_b32 s4, s0, 13
	s_mul_i32 s4, s4, 0x2001
	s_add_i32 s4, s4, 1
	s_lshl_b32 s2, s0, 11
	s_add_u32 s2, s2, 0x8800000
	s_add_u32 s50, s66, s2
	s_addc_u32 s51, s67, 0
	s_and_b32 s0, s0, 0x1fff
	s_add_i32 s3, s0, 1
	v_min_u32_e32 v209, s3, v210
	s_add_i32 s2, s3, 1
	v_min_u32_e32 v208, s2, v210
	s_sub_i32 s0, s3, 0
	s_max_i32 s0, s0, 0
	s_add_i32 s0, s0, s4
	s_lshl_b32 s0, s0, 11
	s_add_u32 s12, s44, s0
	s_addc_u32 s13, s45, 0
	global_load_dwordx4 v[0:3], v211, s[12:13]
	global_load_dwordx4 v[4:7], v211, s[12:13] offset:16
	s_sub_i32 s0, s3, 1
	s_max_i32 s0, s0, 0
	s_add_i32 s0, s0, s4
	s_lshl_b32 s0, s0, 11
	s_add_u32 s12, s44, s0
	s_addc_u32 s13, s45, 0
	global_load_dwordx4 v[8:11], v211, s[12:13]
	global_load_dwordx4 v[12:15], v211, s[12:13] offset:16
	s_sub_i32 s0, s3, 2
	s_max_i32 s0, s0, 0
	s_add_i32 s0, s0, s4
	s_lshl_b32 s0, s0, 11
	s_add_u32 s12, s44, s0
	s_addc_u32 s13, s45, 0
	global_load_dwordx4 v[16:19], v211, s[12:13]
	global_load_dwordx4 v[20:23], v211, s[12:13] offset:16
	s_sub_i32 s0, s3, 3
	s_max_i32 s0, s0, 0
	s_add_i32 s0, s0, s4
	s_lshl_b32 s0, s0, 11
	s_add_u32 s12, s44, s0
	s_addc_u32 s13, s45, 0
	global_load_dwordx4 v[24:27], v211, s[12:13]
	global_load_dwordx4 v[28:31], v211, s[12:13] offset:16
	s_sub_i32 s0, s3, 4
	s_max_i32 s0, s0, 0
	s_add_i32 s0, s0, s4
	s_lshl_b32 s0, s0, 11
	s_add_u32 s12, s44, s0
	s_addc_u32 s13, s45, 0
	global_load_dwordx4 v[32:35], v211, s[12:13]
	global_load_dwordx4 v[36:39], v211, s[12:13] offset:16
	s_sub_i32 s0, s3, 5
	s_max_i32 s0, s0, 0
	s_add_i32 s0, s0, s4
	s_lshl_b32 s0, s0, 11
	s_add_u32 s12, s44, s0
	s_addc_u32 s13, s45, 0
	global_load_dwordx4 v[40:43], v211, s[12:13]
	global_load_dwordx4 v[44:47], v211, s[12:13] offset:16
	s_sub_i32 s0, s3, 6
	s_max_i32 s0, s0, 0
	s_add_i32 s0, s0, s4
	s_lshl_b32 s0, s0, 11
	s_add_u32 s12, s44, s0
	s_addc_u32 s13, s45, 0
	global_load_dwordx4 v[48:51], v211, s[12:13]
	global_load_dwordx4 v[52:55], v211, s[12:13] offset:16
	s_sub_i32 s0, s3, 7
	s_max_i32 s0, s0, 0
	s_add_i32 s0, s0, s4
	s_lshl_b32 s0, s0, 11
	s_add_u32 s12, s44, s0
	s_addc_u32 s13, s45, 0
	global_load_dwordx4 v[56:59], v211, s[12:13]
	global_load_dwordx4 v[60:63], v211, s[12:13] offset:16
	s_sub_i32 s0, s3, 8
	s_max_i32 s0, s0, 0
	s_add_i32 s0, s0, s4
	s_lshl_b32 s0, s0, 11
	s_add_u32 s12, s44, s0
	s_addc_u32 s13, s45, 0
	global_load_dwordx4 v[64:67], v211, s[12:13]
	global_load_dwordx4 v[68:71], v211, s[12:13] offset:16
	s_sub_i32 s0, s3, 9
	s_max_i32 s0, s0, 0
	s_add_i32 s0, s0, s4
	s_lshl_b32 s0, s0, 11
	s_add_u32 s12, s44, s0
	s_addc_u32 s13, s45, 0
	global_load_dwordx4 v[72:75], v211, s[12:13]
	global_load_dwordx4 v[76:79], v211, s[12:13] offset:16
	s_sub_i32 s0, s3, 10
	s_max_i32 s0, s0, 0
	s_add_i32 s0, s0, s4
	s_lshl_b32 s0, s0, 11
	s_add_u32 s12, s44, s0
	s_addc_u32 s13, s45, 0
	global_load_dwordx4 v[80:83], v211, s[12:13]
	global_load_dwordx4 v[84:87], v211, s[12:13] offset:16
	s_sub_i32 s0, s3, 11
	s_max_i32 s0, s0, 0
	s_add_i32 s0, s0, s4
	s_lshl_b32 s0, s0, 11
	s_add_u32 s12, s44, s0
	s_addc_u32 s13, s45, 0
	global_load_dwordx4 v[88:91], v211, s[12:13]
	global_load_dwordx4 v[92:95], v211, s[12:13] offset:16
	s_sub_i32 s0, s3, 12
	s_max_i32 s0, s0, 0
	s_add_i32 s0, s0, s4
	s_lshl_b32 s0, s0, 11
	s_add_u32 s12, s44, s0
	s_addc_u32 s13, s45, 0
	global_load_dwordx4 v[96:99], v211, s[12:13]
	global_load_dwordx4 v[100:103], v211, s[12:13] offset:16
	s_sub_i32 s0, s3, 13
	s_max_i32 s0, s0, 0
	s_add_i32 s0, s0, s4
	s_lshl_b32 s0, s0, 11
	s_add_u32 s12, s44, s0
	s_addc_u32 s13, s45, 0
	global_load_dwordx4 v[104:107], v211, s[12:13]
	global_load_dwordx4 v[108:111], v211, s[12:13] offset:16
	s_sub_i32 s0, s3, 14
	s_max_i32 s0, s0, 0
	s_add_i32 s0, s0, s4
	s_lshl_b32 s0, s0, 11
	s_add_u32 s12, s44, s0
	s_addc_u32 s13, s45, 0
	global_load_dwordx4 v[112:115], v211, s[12:13]
	global_load_dwordx4 v[116:119], v211, s[12:13] offset:16
	s_sub_i32 s0, s3, 15
	s_max_i32 s0, s0, 0
	s_add_i32 s0, s0, s4
	s_lshl_b32 s0, s0, 11
	s_add_u32 s12, s44, s0
	s_addc_u32 s13, s45, 0
	global_load_dwordx4 v[120:123], v211, s[12:13]
	global_load_dwordx4 v[124:127], v211, s[12:13] offset:16
	s_sub_i32 s0, s3, 16
	s_max_i32 s0, s0, 0
	s_add_i32 s0, s0, s4
	s_lshl_b32 s0, s0, 11
	s_add_u32 s12, s44, s0
	s_addc_u32 s13, s45, 0
	global_load_dwordx4 v[128:131], v211, s[12:13]
	global_load_dwordx4 v[132:135], v211, s[12:13] offset:16
	s_waitcnt vmcnt(32)
	v_cmp_lt_u32_e32 vcc, 0, v208
	v_lshlrev_b32_e32 v188, 16, v0
	v_and_b32_e32 v189, 0xffff0000, v0
	v_lshlrev_b32_e32 v196, 16, v4
	v_and_b32_e32 v197, 0xffff0000, v4
	v_cndmask_b32_e32 v204, 0, v179, vcc
	v_lshlrev_b32_e32 v190, 16, v1
	v_and_b32_e32 v191, 0xffff0000, v1
	v_lshlrev_b32_e32 v198, 16, v5
	v_and_b32_e32 v199, 0xffff0000, v5
	v_lshlrev_b32_e32 v192, 16, v2
	v_and_b32_e32 v193, 0xffff0000, v2
	v_lshlrev_b32_e32 v200, 16, v6
	v_and_b32_e32 v201, 0xffff0000, v6
	v_lshlrev_b32_e32 v194, 16, v3
	v_and_b32_e32 v195, 0xffff0000, v3
	v_lshlrev_b32_e32 v202, 16, v7
	v_and_b32_e32 v203, 0xffff0000, v7
	v_pk_fma_f32 v[136:137], v[188:189], v[204:205], 0 op_sel_hi:[1,0,0]
	v_pk_fma_f32 v[138:139], v[190:191], v[204:205], 0 op_sel_hi:[1,0,0]
	v_pk_fma_f32 v[140:141], v[192:193], v[204:205], 0 op_sel_hi:[1,0,0]
	v_pk_fma_f32 v[142:143], v[194:195], v[204:205], 0 op_sel_hi:[1,0,0]
	v_pk_fma_f32 v[144:145], v[196:197], v[204:205], 0 op_sel_hi:[1,0,0]
	v_pk_fma_f32 v[146:147], v[198:199], v[204:205], 0 op_sel_hi:[1,0,0]
	v_pk_fma_f32 v[148:149], v[200:201], v[204:205], 0 op_sel_hi:[1,0,0]
	v_pk_fma_f32 v[150:151], v[202:203], v[204:205], 0 op_sel_hi:[1,0,0]
	s_waitcnt vmcnt(30)
	v_cmp_lt_u32_e32 vcc, 1, v208
	v_lshlrev_b32_e32 v188, 16, v8
	v_and_b32_e32 v189, 0xffff0000, v8
	v_lshlrev_b32_e32 v196, 16, v12
	v_and_b32_e32 v197, 0xffff0000, v12
	v_cndmask_b32_e32 v204, 0, v179, vcc
	v_cmp_lt_u32_e32 vcc, 0, v209
	v_lshlrev_b32_e32 v190, 16, v9
	v_and_b32_e32 v191, 0xffff0000, v9
	v_lshlrev_b32_e32 v198, 16, v13
	v_and_b32_e32 v199, 0xffff0000, v13
	v_lshlrev_b32_e32 v192, 16, v10
	v_and_b32_e32 v193, 0xffff0000, v10
	v_lshlrev_b32_e32 v200, 16, v14
	v_and_b32_e32 v201, 0xffff0000, v14
	v_lshlrev_b32_e32 v194, 16, v11
	v_and_b32_e32 v195, 0xffff0000, v11
	v_lshlrev_b32_e32 v202, 16, v15
	v_and_b32_e32 v203, 0xffff0000, v15
	v_cndmask_b32_e32 v206, 0, v179, vcc
	v_pk_fma_f32 v[136:137], v[188:189], v[204:205], v[136:137] op_sel_hi:[1,0,1]
	v_pk_fma_f32 v[138:139], v[190:191], v[204:205], v[138:139] op_sel_hi:[1,0,1]
	v_pk_fma_f32 v[140:141], v[192:193], v[204:205], v[140:141] op_sel_hi:[1,0,1]
	v_pk_fma_f32 v[142:143], v[194:195], v[204:205], v[142:143] op_sel_hi:[1,0,1]
	v_pk_fma_f32 v[144:145], v[196:197], v[204:205], v[144:145] op_sel_hi:[1,0,1]
	v_pk_fma_f32 v[146:147], v[198:199], v[204:205], v[146:147] op_sel_hi:[1,0,1]
	v_pk_fma_f32 v[148:149], v[200:201], v[204:205], v[148:149] op_sel_hi:[1,0,1]
	v_pk_fma_f32 v[150:151], v[202:203], v[204:205], v[150:151] op_sel_hi:[1,0,1]
	v_pk_fma_f32 v[152:153], v[188:189], v[206:207], 0 op_sel_hi:[1,0,0]
	v_pk_fma_f32 v[154:155], v[190:191], v[206:207], 0 op_sel_hi:[1,0,0]
	v_pk_fma_f32 v[156:157], v[192:193], v[206:207], 0 op_sel_hi:[1,0,0]
	v_pk_fma_f32 v[158:159], v[194:195], v[206:207], 0 op_sel_hi:[1,0,0]
	v_pk_fma_f32 v[160:161], v[196:197], v[206:207], 0 op_sel_hi:[1,0,0]
	v_pk_fma_f32 v[162:163], v[198:199], v[206:207], 0 op_sel_hi:[1,0,0]
	v_pk_fma_f32 v[164:165], v[200:201], v[206:207], 0 op_sel_hi:[1,0,0]
	v_pk_fma_f32 v[166:167], v[202:203], v[206:207], 0 op_sel_hi:[1,0,0]
	s_waitcnt vmcnt(28)
	v_cmp_lt_u32_e32 vcc, 2, v208
	v_lshlrev_b32_e32 v188, 16, v16
	v_and_b32_e32 v189, 0xffff0000, v16
	v_lshlrev_b32_e32 v196, 16, v20
	v_and_b32_e32 v197, 0xffff0000, v20
	v_cndmask_b32_e32 v204, 0, v179, vcc
	v_cmp_lt_u32_e32 vcc, 1, v209
	v_lshlrev_b32_e32 v190, 16, v17
	v_and_b32_e32 v191, 0xffff0000, v17
	v_lshlrev_b32_e32 v198, 16, v21
	v_and_b32_e32 v199, 0xffff0000, v21
	v_lshlrev_b32_e32 v192, 16, v18
	v_and_b32_e32 v193, 0xffff0000, v18
	v_lshlrev_b32_e32 v200, 16, v22
	v_and_b32_e32 v201, 0xffff0000, v22
	v_lshlrev_b32_e32 v194, 16, v19
	v_and_b32_e32 v195, 0xffff0000, v19
	v_lshlrev_b32_e32 v202, 16, v23
	v_and_b32_e32 v203, 0xffff0000, v23
	v_cndmask_b32_e32 v206, 0, v179, vcc
	v_pk_fma_f32 v[136:137], v[188:189], v[204:205], v[136:137] op_sel_hi:[1,0,1]
	v_pk_fma_f32 v[138:139], v[190:191], v[204:205], v[138:139] op_sel_hi:[1,0,1]
	v_pk_fma_f32 v[140:141], v[192:193], v[204:205], v[140:141] op_sel_hi:[1,0,1]
	v_pk_fma_f32 v[142:143], v[194:195], v[204:205], v[142:143] op_sel_hi:[1,0,1]
	v_pk_fma_f32 v[144:145], v[196:197], v[204:205], v[144:145] op_sel_hi:[1,0,1]
	v_pk_fma_f32 v[146:147], v[198:199], v[204:205], v[146:147] op_sel_hi:[1,0,1]
	v_pk_fma_f32 v[148:149], v[200:201], v[204:205], v[148:149] op_sel_hi:[1,0,1]
	v_pk_fma_f32 v[150:151], v[202:203], v[204:205], v[150:151] op_sel_hi:[1,0,1]
	v_pk_fma_f32 v[152:153], v[188:189], v[206:207], v[152:153] op_sel_hi:[1,0,1]
	v_pk_fma_f32 v[154:155], v[190:191], v[206:207], v[154:155] op_sel_hi:[1,0,1]
	v_pk_fma_f32 v[156:157], v[192:193], v[206:207], v[156:157] op_sel_hi:[1,0,1]
	v_pk_fma_f32 v[158:159], v[194:195], v[206:207], v[158:159] op_sel_hi:[1,0,1]
	v_pk_fma_f32 v[160:161], v[196:197], v[206:207], v[160:161] op_sel_hi:[1,0,1]
	v_pk_fma_f32 v[162:163], v[198:199], v[206:207], v[162:163] op_sel_hi:[1,0,1]
	v_pk_fma_f32 v[164:165], v[200:201], v[206:207], v[164:165] op_sel_hi:[1,0,1]
	v_pk_fma_f32 v[166:167], v[202:203], v[206:207], v[166:167] op_sel_hi:[1,0,1]
	s_waitcnt vmcnt(26)
	v_cmp_lt_u32_e32 vcc, 3, v208
	v_lshlrev_b32_e32 v188, 16, v24
	v_and_b32_e32 v189, 0xffff0000, v24
	v_lshlrev_b32_e32 v196, 16, v28
	v_and_b32_e32 v197, 0xffff0000, v28
	v_cndmask_b32_e32 v204, 0, v179, vcc
	v_cmp_lt_u32_e32 vcc, 2, v209
	v_lshlrev_b32_e32 v190, 16, v25
	v_and_b32_e32 v191, 0xffff0000, v25
	v_lshlrev_b32_e32 v198, 16, v29
	v_and_b32_e32 v199, 0xffff0000, v29
	v_lshlrev_b32_e32 v192, 16, v26
	v_and_b32_e32 v193, 0xffff0000, v26
	v_lshlrev_b32_e32 v200, 16, v30
	v_and_b32_e32 v201, 0xffff0000, v30
	v_lshlrev_b32_e32 v194, 16, v27
	v_and_b32_e32 v195, 0xffff0000, v27
	v_lshlrev_b32_e32 v202, 16, v31
	v_and_b32_e32 v203, 0xffff0000, v31
	v_cndmask_b32_e32 v206, 0, v179, vcc
	v_pk_fma_f32 v[136:137], v[188:189], v[204:205], v[136:137] op_sel_hi:[1,0,1]
	v_pk_fma_f32 v[138:139], v[190:191], v[204:205], v[138:139] op_sel_hi:[1,0,1]
	v_pk_fma_f32 v[140:141], v[192:193], v[204:205], v[140:141] op_sel_hi:[1,0,1]
	v_pk_fma_f32 v[142:143], v[194:195], v[204:205], v[142:143] op_sel_hi:[1,0,1]
	v_pk_fma_f32 v[144:145], v[196:197], v[204:205], v[144:145] op_sel_hi:[1,0,1]
	v_pk_fma_f32 v[146:147], v[198:199], v[204:205], v[146:147] op_sel_hi:[1,0,1]
	v_pk_fma_f32 v[148:149], v[200:201], v[204:205], v[148:149] op_sel_hi:[1,0,1]
	v_pk_fma_f32 v[150:151], v[202:203], v[204:205], v[150:151] op_sel_hi:[1,0,1]
	v_pk_fma_f32 v[152:153], v[188:189], v[206:207], v[152:153] op_sel_hi:[1,0,1]
	v_pk_fma_f32 v[154:155], v[190:191], v[206:207], v[154:155] op_sel_hi:[1,0,1]
	v_pk_fma_f32 v[156:157], v[192:193], v[206:207], v[156:157] op_sel_hi:[1,0,1]
	v_pk_fma_f32 v[158:159], v[194:195], v[206:207], v[158:159] op_sel_hi:[1,0,1]
	v_pk_fma_f32 v[160:161], v[196:197], v[206:207], v[160:161] op_sel_hi:[1,0,1]
	v_pk_fma_f32 v[162:163], v[198:199], v[206:207], v[162:163] op_sel_hi:[1,0,1]
	v_pk_fma_f32 v[164:165], v[200:201], v[206:207], v[164:165] op_sel_hi:[1,0,1]
	v_pk_fma_f32 v[166:167], v[202:203], v[206:207], v[166:167] op_sel_hi:[1,0,1]
	s_waitcnt vmcnt(24)
	v_cmp_lt_u32_e32 vcc, 4, v208
	v_lshlrev_b32_e32 v188, 16, v32
	v_and_b32_e32 v189, 0xffff0000, v32
	v_lshlrev_b32_e32 v196, 16, v36
	v_and_b32_e32 v197, 0xffff0000, v36
	v_cndmask_b32_e32 v204, 0, v179, vcc
	v_cmp_lt_u32_e32 vcc, 3, v209
	v_lshlrev_b32_e32 v190, 16, v33
	v_and_b32_e32 v191, 0xffff0000, v33
	v_lshlrev_b32_e32 v198, 16, v37
	v_and_b32_e32 v199, 0xffff0000, v37
	v_lshlrev_b32_e32 v192, 16, v34
	v_and_b32_e32 v193, 0xffff0000, v34
	v_lshlrev_b32_e32 v200, 16, v38
	v_and_b32_e32 v201, 0xffff0000, v38
	v_lshlrev_b32_e32 v194, 16, v35
	v_and_b32_e32 v195, 0xffff0000, v35
	v_lshlrev_b32_e32 v202, 16, v39
	v_and_b32_e32 v203, 0xffff0000, v39
	v_cndmask_b32_e32 v206, 0, v179, vcc
	v_pk_fma_f32 v[136:137], v[188:189], v[204:205], v[136:137] op_sel_hi:[1,0,1]
	v_pk_fma_f32 v[138:139], v[190:191], v[204:205], v[138:139] op_sel_hi:[1,0,1]
	v_pk_fma_f32 v[140:141], v[192:193], v[204:205], v[140:141] op_sel_hi:[1,0,1]
	v_pk_fma_f32 v[142:143], v[194:195], v[204:205], v[142:143] op_sel_hi:[1,0,1]
	v_pk_fma_f32 v[144:145], v[196:197], v[204:205], v[144:145] op_sel_hi:[1,0,1]
	v_pk_fma_f32 v[146:147], v[198:199], v[204:205], v[146:147] op_sel_hi:[1,0,1]
	v_pk_fma_f32 v[148:149], v[200:201], v[204:205], v[148:149] op_sel_hi:[1,0,1]
	v_pk_fma_f32 v[150:151], v[202:203], v[204:205], v[150:151] op_sel_hi:[1,0,1]
	v_pk_fma_f32 v[152:153], v[188:189], v[206:207], v[152:153] op_sel_hi:[1,0,1]
	v_pk_fma_f32 v[154:155], v[190:191], v[206:207], v[154:155] op_sel_hi:[1,0,1]
	v_pk_fma_f32 v[156:157], v[192:193], v[206:207], v[156:157] op_sel_hi:[1,0,1]
	v_pk_fma_f32 v[158:159], v[194:195], v[206:207], v[158:159] op_sel_hi:[1,0,1]
	v_pk_fma_f32 v[160:161], v[196:197], v[206:207], v[160:161] op_sel_hi:[1,0,1]
	v_pk_fma_f32 v[162:163], v[198:199], v[206:207], v[162:163] op_sel_hi:[1,0,1]
	v_pk_fma_f32 v[164:165], v[200:201], v[206:207], v[164:165] op_sel_hi:[1,0,1]
	v_pk_fma_f32 v[166:167], v[202:203], v[206:207], v[166:167] op_sel_hi:[1,0,1]
	s_waitcnt vmcnt(22)
	v_cmp_lt_u32_e32 vcc, 5, v208
	v_lshlrev_b32_e32 v188, 16, v40
	v_and_b32_e32 v189, 0xffff0000, v40
	v_lshlrev_b32_e32 v196, 16, v44
	v_and_b32_e32 v197, 0xffff0000, v44
	v_cndmask_b32_e32 v204, 0, v179, vcc
	v_cmp_lt_u32_e32 vcc, 4, v209
	v_lshlrev_b32_e32 v190, 16, v41
	v_and_b32_e32 v191, 0xffff0000, v41
	v_lshlrev_b32_e32 v198, 16, v45
	v_and_b32_e32 v199, 0xffff0000, v45
	v_lshlrev_b32_e32 v192, 16, v42
	v_and_b32_e32 v193, 0xffff0000, v42
	v_lshlrev_b32_e32 v200, 16, v46
	v_and_b32_e32 v201, 0xffff0000, v46
	v_lshlrev_b32_e32 v194, 16, v43
	v_and_b32_e32 v195, 0xffff0000, v43
	v_lshlrev_b32_e32 v202, 16, v47
	v_and_b32_e32 v203, 0xffff0000, v47
	v_cndmask_b32_e32 v206, 0, v179, vcc
	v_pk_fma_f32 v[136:137], v[188:189], v[204:205], v[136:137] op_sel_hi:[1,0,1]
	v_pk_fma_f32 v[138:139], v[190:191], v[204:205], v[138:139] op_sel_hi:[1,0,1]
	v_pk_fma_f32 v[140:141], v[192:193], v[204:205], v[140:141] op_sel_hi:[1,0,1]
	v_pk_fma_f32 v[142:143], v[194:195], v[204:205], v[142:143] op_sel_hi:[1,0,1]
	v_pk_fma_f32 v[144:145], v[196:197], v[204:205], v[144:145] op_sel_hi:[1,0,1]
	v_pk_fma_f32 v[146:147], v[198:199], v[204:205], v[146:147] op_sel_hi:[1,0,1]
	v_pk_fma_f32 v[148:149], v[200:201], v[204:205], v[148:149] op_sel_hi:[1,0,1]
	v_pk_fma_f32 v[150:151], v[202:203], v[204:205], v[150:151] op_sel_hi:[1,0,1]
	v_pk_fma_f32 v[152:153], v[188:189], v[206:207], v[152:153] op_sel_hi:[1,0,1]
	v_pk_fma_f32 v[154:155], v[190:191], v[206:207], v[154:155] op_sel_hi:[1,0,1]
	v_pk_fma_f32 v[156:157], v[192:193], v[206:207], v[156:157] op_sel_hi:[1,0,1]
	v_pk_fma_f32 v[158:159], v[194:195], v[206:207], v[158:159] op_sel_hi:[1,0,1]
	v_pk_fma_f32 v[160:161], v[196:197], v[206:207], v[160:161] op_sel_hi:[1,0,1]
	v_pk_fma_f32 v[162:163], v[198:199], v[206:207], v[162:163] op_sel_hi:[1,0,1]
	v_pk_fma_f32 v[164:165], v[200:201], v[206:207], v[164:165] op_sel_hi:[1,0,1]
	v_pk_fma_f32 v[166:167], v[202:203], v[206:207], v[166:167] op_sel_hi:[1,0,1]
	s_waitcnt vmcnt(20)
	v_cmp_lt_u32_e32 vcc, 6, v208
	v_lshlrev_b32_e32 v188, 16, v48
	v_and_b32_e32 v189, 0xffff0000, v48
	v_lshlrev_b32_e32 v196, 16, v52
	v_and_b32_e32 v197, 0xffff0000, v52
	v_cndmask_b32_e32 v204, 0, v179, vcc
	v_cmp_lt_u32_e32 vcc, 5, v209
	v_lshlrev_b32_e32 v190, 16, v49
	v_and_b32_e32 v191, 0xffff0000, v49
	v_lshlrev_b32_e32 v198, 16, v53
	v_and_b32_e32 v199, 0xffff0000, v53
	v_lshlrev_b32_e32 v192, 16, v50
	v_and_b32_e32 v193, 0xffff0000, v50
	v_lshlrev_b32_e32 v200, 16, v54
	v_and_b32_e32 v201, 0xffff0000, v54
	v_lshlrev_b32_e32 v194, 16, v51
	v_and_b32_e32 v195, 0xffff0000, v51
	v_lshlrev_b32_e32 v202, 16, v55
	v_and_b32_e32 v203, 0xffff0000, v55
	v_cndmask_b32_e32 v206, 0, v179, vcc
	v_pk_fma_f32 v[136:137], v[188:189], v[204:205], v[136:137] op_sel_hi:[1,0,1]
	v_pk_fma_f32 v[138:139], v[190:191], v[204:205], v[138:139] op_sel_hi:[1,0,1]
	v_pk_fma_f32 v[140:141], v[192:193], v[204:205], v[140:141] op_sel_hi:[1,0,1]
	v_pk_fma_f32 v[142:143], v[194:195], v[204:205], v[142:143] op_sel_hi:[1,0,1]
	v_pk_fma_f32 v[144:145], v[196:197], v[204:205], v[144:145] op_sel_hi:[1,0,1]
	v_pk_fma_f32 v[146:147], v[198:199], v[204:205], v[146:147] op_sel_hi:[1,0,1]
	v_pk_fma_f32 v[148:149], v[200:201], v[204:205], v[148:149] op_sel_hi:[1,0,1]
	v_pk_fma_f32 v[150:151], v[202:203], v[204:205], v[150:151] op_sel_hi:[1,0,1]
	v_pk_fma_f32 v[152:153], v[188:189], v[206:207], v[152:153] op_sel_hi:[1,0,1]
	v_pk_fma_f32 v[154:155], v[190:191], v[206:207], v[154:155] op_sel_hi:[1,0,1]
	v_pk_fma_f32 v[156:157], v[192:193], v[206:207], v[156:157] op_sel_hi:[1,0,1]
	v_pk_fma_f32 v[158:159], v[194:195], v[206:207], v[158:159] op_sel_hi:[1,0,1]
	v_pk_fma_f32 v[160:161], v[196:197], v[206:207], v[160:161] op_sel_hi:[1,0,1]
	v_pk_fma_f32 v[162:163], v[198:199], v[206:207], v[162:163] op_sel_hi:[1,0,1]
	v_pk_fma_f32 v[164:165], v[200:201], v[206:207], v[164:165] op_sel_hi:[1,0,1]
	v_pk_fma_f32 v[166:167], v[202:203], v[206:207], v[166:167] op_sel_hi:[1,0,1]
	s_waitcnt vmcnt(18)
	v_cmp_lt_u32_e32 vcc, 7, v208
	v_lshlrev_b32_e32 v188, 16, v56
	v_and_b32_e32 v189, 0xffff0000, v56
	v_lshlrev_b32_e32 v196, 16, v60
	v_and_b32_e32 v197, 0xffff0000, v60
	v_cndmask_b32_e32 v204, 0, v179, vcc
	v_cmp_lt_u32_e32 vcc, 6, v209
	v_lshlrev_b32_e32 v190, 16, v57
	v_and_b32_e32 v191, 0xffff0000, v57
	v_lshlrev_b32_e32 v198, 16, v61
	v_and_b32_e32 v199, 0xffff0000, v61
	v_lshlrev_b32_e32 v192, 16, v58
	v_and_b32_e32 v193, 0xffff0000, v58
	v_lshlrev_b32_e32 v200, 16, v62
	v_and_b32_e32 v201, 0xffff0000, v62
	v_lshlrev_b32_e32 v194, 16, v59
	v_and_b32_e32 v195, 0xffff0000, v59
	v_lshlrev_b32_e32 v202, 16, v63
	v_and_b32_e32 v203, 0xffff0000, v63
	v_cndmask_b32_e32 v206, 0, v179, vcc
	v_pk_fma_f32 v[136:137], v[188:189], v[204:205], v[136:137] op_sel_hi:[1,0,1]
	v_pk_fma_f32 v[138:139], v[190:191], v[204:205], v[138:139] op_sel_hi:[1,0,1]
	v_pk_fma_f32 v[140:141], v[192:193], v[204:205], v[140:141] op_sel_hi:[1,0,1]
	v_pk_fma_f32 v[142:143], v[194:195], v[204:205], v[142:143] op_sel_hi:[1,0,1]
	v_pk_fma_f32 v[144:145], v[196:197], v[204:205], v[144:145] op_sel_hi:[1,0,1]
	v_pk_fma_f32 v[146:147], v[198:199], v[204:205], v[146:147] op_sel_hi:[1,0,1]
	v_pk_fma_f32 v[148:149], v[200:201], v[204:205], v[148:149] op_sel_hi:[1,0,1]
	v_pk_fma_f32 v[150:151], v[202:203], v[204:205], v[150:151] op_sel_hi:[1,0,1]
	v_pk_fma_f32 v[152:153], v[188:189], v[206:207], v[152:153] op_sel_hi:[1,0,1]
	v_pk_fma_f32 v[154:155], v[190:191], v[206:207], v[154:155] op_sel_hi:[1,0,1]
	v_pk_fma_f32 v[156:157], v[192:193], v[206:207], v[156:157] op_sel_hi:[1,0,1]
	v_pk_fma_f32 v[158:159], v[194:195], v[206:207], v[158:159] op_sel_hi:[1,0,1]
	v_pk_fma_f32 v[160:161], v[196:197], v[206:207], v[160:161] op_sel_hi:[1,0,1]
	v_pk_fma_f32 v[162:163], v[198:199], v[206:207], v[162:163] op_sel_hi:[1,0,1]
	v_pk_fma_f32 v[164:165], v[200:201], v[206:207], v[164:165] op_sel_hi:[1,0,1]
	v_pk_fma_f32 v[166:167], v[202:203], v[206:207], v[166:167] op_sel_hi:[1,0,1]
	s_waitcnt vmcnt(16)
	v_cmp_lt_u32_e32 vcc, 8, v208
	v_lshlrev_b32_e32 v188, 16, v64
	v_and_b32_e32 v189, 0xffff0000, v64
	v_lshlrev_b32_e32 v196, 16, v68
	v_and_b32_e32 v197, 0xffff0000, v68
	v_cndmask_b32_e32 v204, 0, v179, vcc
	v_cmp_lt_u32_e32 vcc, 7, v209
	v_lshlrev_b32_e32 v190, 16, v65
	v_and_b32_e32 v191, 0xffff0000, v65
	v_lshlrev_b32_e32 v198, 16, v69
	v_and_b32_e32 v199, 0xffff0000, v69
	v_lshlrev_b32_e32 v192, 16, v66
	v_and_b32_e32 v193, 0xffff0000, v66
	v_lshlrev_b32_e32 v200, 16, v70
	v_and_b32_e32 v201, 0xffff0000, v70
	v_lshlrev_b32_e32 v194, 16, v67
	v_and_b32_e32 v195, 0xffff0000, v67
	v_lshlrev_b32_e32 v202, 16, v71
	v_and_b32_e32 v203, 0xffff0000, v71
	v_cndmask_b32_e32 v206, 0, v179, vcc
	v_pk_fma_f32 v[136:137], v[188:189], v[204:205], v[136:137] op_sel_hi:[1,0,1]
	v_pk_fma_f32 v[138:139], v[190:191], v[204:205], v[138:139] op_sel_hi:[1,0,1]
	v_pk_fma_f32 v[140:141], v[192:193], v[204:205], v[140:141] op_sel_hi:[1,0,1]
	v_pk_fma_f32 v[142:143], v[194:195], v[204:205], v[142:143] op_sel_hi:[1,0,1]
	v_pk_fma_f32 v[144:145], v[196:197], v[204:205], v[144:145] op_sel_hi:[1,0,1]
	v_pk_fma_f32 v[146:147], v[198:199], v[204:205], v[146:147] op_sel_hi:[1,0,1]
	v_pk_fma_f32 v[148:149], v[200:201], v[204:205], v[148:149] op_sel_hi:[1,0,1]
	v_pk_fma_f32 v[150:151], v[202:203], v[204:205], v[150:151] op_sel_hi:[1,0,1]
	v_pk_fma_f32 v[152:153], v[188:189], v[206:207], v[152:153] op_sel_hi:[1,0,1]
	v_pk_fma_f32 v[154:155], v[190:191], v[206:207], v[154:155] op_sel_hi:[1,0,1]
	v_pk_fma_f32 v[156:157], v[192:193], v[206:207], v[156:157] op_sel_hi:[1,0,1]
	v_pk_fma_f32 v[158:159], v[194:195], v[206:207], v[158:159] op_sel_hi:[1,0,1]
	v_pk_fma_f32 v[160:161], v[196:197], v[206:207], v[160:161] op_sel_hi:[1,0,1]
	v_pk_fma_f32 v[162:163], v[198:199], v[206:207], v[162:163] op_sel_hi:[1,0,1]
	v_pk_fma_f32 v[164:165], v[200:201], v[206:207], v[164:165] op_sel_hi:[1,0,1]
	v_pk_fma_f32 v[166:167], v[202:203], v[206:207], v[166:167] op_sel_hi:[1,0,1]
	s_waitcnt vmcnt(14)
	v_cmp_lt_u32_e32 vcc, 9, v208
	v_lshlrev_b32_e32 v188, 16, v72
	v_and_b32_e32 v189, 0xffff0000, v72
	v_lshlrev_b32_e32 v196, 16, v76
	v_and_b32_e32 v197, 0xffff0000, v76
	v_cndmask_b32_e32 v204, 0, v179, vcc
	v_cmp_lt_u32_e32 vcc, 8, v209
	v_lshlrev_b32_e32 v190, 16, v73
	v_and_b32_e32 v191, 0xffff0000, v73
	v_lshlrev_b32_e32 v198, 16, v77
	v_and_b32_e32 v199, 0xffff0000, v77
	v_lshlrev_b32_e32 v192, 16, v74
	v_and_b32_e32 v193, 0xffff0000, v74
	v_lshlrev_b32_e32 v200, 16, v78
	v_and_b32_e32 v201, 0xffff0000, v78
	v_lshlrev_b32_e32 v194, 16, v75
	v_and_b32_e32 v195, 0xffff0000, v75
	v_lshlrev_b32_e32 v202, 16, v79
	v_and_b32_e32 v203, 0xffff0000, v79
	v_cndmask_b32_e32 v206, 0, v179, vcc
	v_pk_fma_f32 v[136:137], v[188:189], v[204:205], v[136:137] op_sel_hi:[1,0,1]
	v_pk_fma_f32 v[138:139], v[190:191], v[204:205], v[138:139] op_sel_hi:[1,0,1]
	v_pk_fma_f32 v[140:141], v[192:193], v[204:205], v[140:141] op_sel_hi:[1,0,1]
	v_pk_fma_f32 v[142:143], v[194:195], v[204:205], v[142:143] op_sel_hi:[1,0,1]
	v_pk_fma_f32 v[144:145], v[196:197], v[204:205], v[144:145] op_sel_hi:[1,0,1]
	v_pk_fma_f32 v[146:147], v[198:199], v[204:205], v[146:147] op_sel_hi:[1,0,1]
	v_pk_fma_f32 v[148:149], v[200:201], v[204:205], v[148:149] op_sel_hi:[1,0,1]
	v_pk_fma_f32 v[150:151], v[202:203], v[204:205], v[150:151] op_sel_hi:[1,0,1]
	v_pk_fma_f32 v[152:153], v[188:189], v[206:207], v[152:153] op_sel_hi:[1,0,1]
	v_pk_fma_f32 v[154:155], v[190:191], v[206:207], v[154:155] op_sel_hi:[1,0,1]
	v_pk_fma_f32 v[156:157], v[192:193], v[206:207], v[156:157] op_sel_hi:[1,0,1]
	v_pk_fma_f32 v[158:159], v[194:195], v[206:207], v[158:159] op_sel_hi:[1,0,1]
	v_pk_fma_f32 v[160:161], v[196:197], v[206:207], v[160:161] op_sel_hi:[1,0,1]
	v_pk_fma_f32 v[162:163], v[198:199], v[206:207], v[162:163] op_sel_hi:[1,0,1]
	v_pk_fma_f32 v[164:165], v[200:201], v[206:207], v[164:165] op_sel_hi:[1,0,1]
	v_pk_fma_f32 v[166:167], v[202:203], v[206:207], v[166:167] op_sel_hi:[1,0,1]
	s_waitcnt vmcnt(12)
	v_cmp_lt_u32_e32 vcc, 10, v208
	v_lshlrev_b32_e32 v188, 16, v80
	v_and_b32_e32 v189, 0xffff0000, v80
	v_lshlrev_b32_e32 v196, 16, v84
	v_and_b32_e32 v197, 0xffff0000, v84
	v_cndmask_b32_e32 v204, 0, v179, vcc
	v_cmp_lt_u32_e32 vcc, 9, v209
	v_lshlrev_b32_e32 v190, 16, v81
	v_and_b32_e32 v191, 0xffff0000, v81
	v_lshlrev_b32_e32 v198, 16, v85
	v_and_b32_e32 v199, 0xffff0000, v85
	v_lshlrev_b32_e32 v192, 16, v82
	v_and_b32_e32 v193, 0xffff0000, v82
	v_lshlrev_b32_e32 v200, 16, v86
	v_and_b32_e32 v201, 0xffff0000, v86
	v_lshlrev_b32_e32 v194, 16, v83
	v_and_b32_e32 v195, 0xffff0000, v83
	v_lshlrev_b32_e32 v202, 16, v87
	v_and_b32_e32 v203, 0xffff0000, v87
	v_cndmask_b32_e32 v206, 0, v179, vcc
	v_pk_fma_f32 v[136:137], v[188:189], v[204:205], v[136:137] op_sel_hi:[1,0,1]
	v_pk_fma_f32 v[138:139], v[190:191], v[204:205], v[138:139] op_sel_hi:[1,0,1]
	v_pk_fma_f32 v[140:141], v[192:193], v[204:205], v[140:141] op_sel_hi:[1,0,1]
	v_pk_fma_f32 v[142:143], v[194:195], v[204:205], v[142:143] op_sel_hi:[1,0,1]
	v_pk_fma_f32 v[144:145], v[196:197], v[204:205], v[144:145] op_sel_hi:[1,0,1]
	v_pk_fma_f32 v[146:147], v[198:199], v[204:205], v[146:147] op_sel_hi:[1,0,1]
	v_pk_fma_f32 v[148:149], v[200:201], v[204:205], v[148:149] op_sel_hi:[1,0,1]
	v_pk_fma_f32 v[150:151], v[202:203], v[204:205], v[150:151] op_sel_hi:[1,0,1]
	v_pk_fma_f32 v[152:153], v[188:189], v[206:207], v[152:153] op_sel_hi:[1,0,1]
	v_pk_fma_f32 v[154:155], v[190:191], v[206:207], v[154:155] op_sel_hi:[1,0,1]
	v_pk_fma_f32 v[156:157], v[192:193], v[206:207], v[156:157] op_sel_hi:[1,0,1]
	v_pk_fma_f32 v[158:159], v[194:195], v[206:207], v[158:159] op_sel_hi:[1,0,1]
	v_pk_fma_f32 v[160:161], v[196:197], v[206:207], v[160:161] op_sel_hi:[1,0,1]
	v_pk_fma_f32 v[162:163], v[198:199], v[206:207], v[162:163] op_sel_hi:[1,0,1]
	v_pk_fma_f32 v[164:165], v[200:201], v[206:207], v[164:165] op_sel_hi:[1,0,1]
	v_pk_fma_f32 v[166:167], v[202:203], v[206:207], v[166:167] op_sel_hi:[1,0,1]
	s_waitcnt vmcnt(10)
	v_cmp_lt_u32_e32 vcc, 11, v208
	v_lshlrev_b32_e32 v188, 16, v88
	v_and_b32_e32 v189, 0xffff0000, v88
	v_lshlrev_b32_e32 v196, 16, v92
	v_and_b32_e32 v197, 0xffff0000, v92
	v_cndmask_b32_e32 v204, 0, v179, vcc
	v_cmp_lt_u32_e32 vcc, 10, v209
	v_lshlrev_b32_e32 v190, 16, v89
	v_and_b32_e32 v191, 0xffff0000, v89
	v_lshlrev_b32_e32 v198, 16, v93
	v_and_b32_e32 v199, 0xffff0000, v93
	v_lshlrev_b32_e32 v192, 16, v90
	v_and_b32_e32 v193, 0xffff0000, v90
	v_lshlrev_b32_e32 v200, 16, v94
	v_and_b32_e32 v201, 0xffff0000, v94
	v_lshlrev_b32_e32 v194, 16, v91
	v_and_b32_e32 v195, 0xffff0000, v91
	v_lshlrev_b32_e32 v202, 16, v95
	v_and_b32_e32 v203, 0xffff0000, v95
	v_cndmask_b32_e32 v206, 0, v179, vcc
	v_pk_fma_f32 v[136:137], v[188:189], v[204:205], v[136:137] op_sel_hi:[1,0,1]
	v_pk_fma_f32 v[138:139], v[190:191], v[204:205], v[138:139] op_sel_hi:[1,0,1]
	v_pk_fma_f32 v[140:141], v[192:193], v[204:205], v[140:141] op_sel_hi:[1,0,1]
	v_pk_fma_f32 v[142:143], v[194:195], v[204:205], v[142:143] op_sel_hi:[1,0,1]
	v_pk_fma_f32 v[144:145], v[196:197], v[204:205], v[144:145] op_sel_hi:[1,0,1]
	v_pk_fma_f32 v[146:147], v[198:199], v[204:205], v[146:147] op_sel_hi:[1,0,1]
	v_pk_fma_f32 v[148:149], v[200:201], v[204:205], v[148:149] op_sel_hi:[1,0,1]
	v_pk_fma_f32 v[150:151], v[202:203], v[204:205], v[150:151] op_sel_hi:[1,0,1]
	v_pk_fma_f32 v[152:153], v[188:189], v[206:207], v[152:153] op_sel_hi:[1,0,1]
	v_pk_fma_f32 v[154:155], v[190:191], v[206:207], v[154:155] op_sel_hi:[1,0,1]
	v_pk_fma_f32 v[156:157], v[192:193], v[206:207], v[156:157] op_sel_hi:[1,0,1]
	v_pk_fma_f32 v[158:159], v[194:195], v[206:207], v[158:159] op_sel_hi:[1,0,1]
	v_pk_fma_f32 v[160:161], v[196:197], v[206:207], v[160:161] op_sel_hi:[1,0,1]
	v_pk_fma_f32 v[162:163], v[198:199], v[206:207], v[162:163] op_sel_hi:[1,0,1]
	v_pk_fma_f32 v[164:165], v[200:201], v[206:207], v[164:165] op_sel_hi:[1,0,1]
	v_pk_fma_f32 v[166:167], v[202:203], v[206:207], v[166:167] op_sel_hi:[1,0,1]
	s_waitcnt vmcnt(8)
	v_cmp_lt_u32_e32 vcc, 12, v208
	v_lshlrev_b32_e32 v188, 16, v96
	v_and_b32_e32 v189, 0xffff0000, v96
	v_lshlrev_b32_e32 v196, 16, v100
	v_and_b32_e32 v197, 0xffff0000, v100
	v_cndmask_b32_e32 v204, 0, v179, vcc
	v_cmp_lt_u32_e32 vcc, 11, v209
	v_lshlrev_b32_e32 v190, 16, v97
	v_and_b32_e32 v191, 0xffff0000, v97
	v_lshlrev_b32_e32 v198, 16, v101
	v_and_b32_e32 v199, 0xffff0000, v101
	v_lshlrev_b32_e32 v192, 16, v98
	v_and_b32_e32 v193, 0xffff0000, v98
	v_lshlrev_b32_e32 v200, 16, v102
	v_and_b32_e32 v201, 0xffff0000, v102
	v_lshlrev_b32_e32 v194, 16, v99
	v_and_b32_e32 v195, 0xffff0000, v99
	v_lshlrev_b32_e32 v202, 16, v103
	v_and_b32_e32 v203, 0xffff0000, v103
	v_cndmask_b32_e32 v206, 0, v179, vcc
	v_pk_fma_f32 v[136:137], v[188:189], v[204:205], v[136:137] op_sel_hi:[1,0,1]
	v_pk_fma_f32 v[138:139], v[190:191], v[204:205], v[138:139] op_sel_hi:[1,0,1]
	v_pk_fma_f32 v[140:141], v[192:193], v[204:205], v[140:141] op_sel_hi:[1,0,1]
	v_pk_fma_f32 v[142:143], v[194:195], v[204:205], v[142:143] op_sel_hi:[1,0,1]
	v_pk_fma_f32 v[144:145], v[196:197], v[204:205], v[144:145] op_sel_hi:[1,0,1]
	v_pk_fma_f32 v[146:147], v[198:199], v[204:205], v[146:147] op_sel_hi:[1,0,1]
	v_pk_fma_f32 v[148:149], v[200:201], v[204:205], v[148:149] op_sel_hi:[1,0,1]
	v_pk_fma_f32 v[150:151], v[202:203], v[204:205], v[150:151] op_sel_hi:[1,0,1]
	v_pk_fma_f32 v[152:153], v[188:189], v[206:207], v[152:153] op_sel_hi:[1,0,1]
	v_pk_fma_f32 v[154:155], v[190:191], v[206:207], v[154:155] op_sel_hi:[1,0,1]
	v_pk_fma_f32 v[156:157], v[192:193], v[206:207], v[156:157] op_sel_hi:[1,0,1]
	v_pk_fma_f32 v[158:159], v[194:195], v[206:207], v[158:159] op_sel_hi:[1,0,1]
	v_pk_fma_f32 v[160:161], v[196:197], v[206:207], v[160:161] op_sel_hi:[1,0,1]
	v_pk_fma_f32 v[162:163], v[198:199], v[206:207], v[162:163] op_sel_hi:[1,0,1]
	v_pk_fma_f32 v[164:165], v[200:201], v[206:207], v[164:165] op_sel_hi:[1,0,1]
	v_pk_fma_f32 v[166:167], v[202:203], v[206:207], v[166:167] op_sel_hi:[1,0,1]
	s_waitcnt vmcnt(6)
	v_cmp_lt_u32_e32 vcc, 13, v208
	v_lshlrev_b32_e32 v188, 16, v104
	v_and_b32_e32 v189, 0xffff0000, v104
	v_lshlrev_b32_e32 v196, 16, v108
	v_and_b32_e32 v197, 0xffff0000, v108
	v_cndmask_b32_e32 v204, 0, v179, vcc
	v_cmp_lt_u32_e32 vcc, 12, v209
	v_lshlrev_b32_e32 v190, 16, v105
	v_and_b32_e32 v191, 0xffff0000, v105
	v_lshlrev_b32_e32 v198, 16, v109
	v_and_b32_e32 v199, 0xffff0000, v109
	v_lshlrev_b32_e32 v192, 16, v106
	v_and_b32_e32 v193, 0xffff0000, v106
	v_lshlrev_b32_e32 v200, 16, v110
	v_and_b32_e32 v201, 0xffff0000, v110
	v_lshlrev_b32_e32 v194, 16, v107
	v_and_b32_e32 v195, 0xffff0000, v107
	v_lshlrev_b32_e32 v202, 16, v111
	v_and_b32_e32 v203, 0xffff0000, v111
	v_cndmask_b32_e32 v206, 0, v179, vcc
	v_pk_fma_f32 v[136:137], v[188:189], v[204:205], v[136:137] op_sel_hi:[1,0,1]
	v_pk_fma_f32 v[138:139], v[190:191], v[204:205], v[138:139] op_sel_hi:[1,0,1]
	v_pk_fma_f32 v[140:141], v[192:193], v[204:205], v[140:141] op_sel_hi:[1,0,1]
	v_pk_fma_f32 v[142:143], v[194:195], v[204:205], v[142:143] op_sel_hi:[1,0,1]
	v_pk_fma_f32 v[144:145], v[196:197], v[204:205], v[144:145] op_sel_hi:[1,0,1]
	v_pk_fma_f32 v[146:147], v[198:199], v[204:205], v[146:147] op_sel_hi:[1,0,1]
	v_pk_fma_f32 v[148:149], v[200:201], v[204:205], v[148:149] op_sel_hi:[1,0,1]
	v_pk_fma_f32 v[150:151], v[202:203], v[204:205], v[150:151] op_sel_hi:[1,0,1]
	v_pk_fma_f32 v[152:153], v[188:189], v[206:207], v[152:153] op_sel_hi:[1,0,1]
	v_pk_fma_f32 v[154:155], v[190:191], v[206:207], v[154:155] op_sel_hi:[1,0,1]
	v_pk_fma_f32 v[156:157], v[192:193], v[206:207], v[156:157] op_sel_hi:[1,0,1]
	v_pk_fma_f32 v[158:159], v[194:195], v[206:207], v[158:159] op_sel_hi:[1,0,1]
	v_pk_fma_f32 v[160:161], v[196:197], v[206:207], v[160:161] op_sel_hi:[1,0,1]
	v_pk_fma_f32 v[162:163], v[198:199], v[206:207], v[162:163] op_sel_hi:[1,0,1]
	v_pk_fma_f32 v[164:165], v[200:201], v[206:207], v[164:165] op_sel_hi:[1,0,1]
	v_pk_fma_f32 v[166:167], v[202:203], v[206:207], v[166:167] op_sel_hi:[1,0,1]
	s_waitcnt vmcnt(4)
	v_cmp_lt_u32_e32 vcc, 14, v208
	v_lshlrev_b32_e32 v188, 16, v112
	v_and_b32_e32 v189, 0xffff0000, v112
	v_lshlrev_b32_e32 v196, 16, v116
	v_and_b32_e32 v197, 0xffff0000, v116
	v_cndmask_b32_e32 v204, 0, v179, vcc
	v_cmp_lt_u32_e32 vcc, 13, v209
	v_lshlrev_b32_e32 v190, 16, v113
	v_and_b32_e32 v191, 0xffff0000, v113
	v_lshlrev_b32_e32 v198, 16, v117
	v_and_b32_e32 v199, 0xffff0000, v117
	v_lshlrev_b32_e32 v192, 16, v114
	v_and_b32_e32 v193, 0xffff0000, v114
	v_lshlrev_b32_e32 v200, 16, v118
	v_and_b32_e32 v201, 0xffff0000, v118
	v_lshlrev_b32_e32 v194, 16, v115
	v_and_b32_e32 v195, 0xffff0000, v115
	v_lshlrev_b32_e32 v202, 16, v119
	v_and_b32_e32 v203, 0xffff0000, v119
	v_cndmask_b32_e32 v206, 0, v179, vcc
	v_pk_fma_f32 v[136:137], v[188:189], v[204:205], v[136:137] op_sel_hi:[1,0,1]
	v_pk_fma_f32 v[138:139], v[190:191], v[204:205], v[138:139] op_sel_hi:[1,0,1]
	v_pk_fma_f32 v[140:141], v[192:193], v[204:205], v[140:141] op_sel_hi:[1,0,1]
	v_pk_fma_f32 v[142:143], v[194:195], v[204:205], v[142:143] op_sel_hi:[1,0,1]
	v_pk_fma_f32 v[144:145], v[196:197], v[204:205], v[144:145] op_sel_hi:[1,0,1]
	v_pk_fma_f32 v[146:147], v[198:199], v[204:205], v[146:147] op_sel_hi:[1,0,1]
	v_pk_fma_f32 v[148:149], v[200:201], v[204:205], v[148:149] op_sel_hi:[1,0,1]
	v_pk_fma_f32 v[150:151], v[202:203], v[204:205], v[150:151] op_sel_hi:[1,0,1]
	v_pk_fma_f32 v[152:153], v[188:189], v[206:207], v[152:153] op_sel_hi:[1,0,1]
	v_pk_fma_f32 v[154:155], v[190:191], v[206:207], v[154:155] op_sel_hi:[1,0,1]
	v_pk_fma_f32 v[156:157], v[192:193], v[206:207], v[156:157] op_sel_hi:[1,0,1]
	v_pk_fma_f32 v[158:159], v[194:195], v[206:207], v[158:159] op_sel_hi:[1,0,1]
	v_pk_fma_f32 v[160:161], v[196:197], v[206:207], v[160:161] op_sel_hi:[1,0,1]
	v_pk_fma_f32 v[162:163], v[198:199], v[206:207], v[162:163] op_sel_hi:[1,0,1]
	v_pk_fma_f32 v[164:165], v[200:201], v[206:207], v[164:165] op_sel_hi:[1,0,1]
	v_pk_fma_f32 v[166:167], v[202:203], v[206:207], v[166:167] op_sel_hi:[1,0,1]
	s_waitcnt vmcnt(2)
	v_cmp_lt_u32_e32 vcc, 15, v208
	v_lshlrev_b32_e32 v188, 16, v120
	v_and_b32_e32 v189, 0xffff0000, v120
	v_lshlrev_b32_e32 v196, 16, v124
	v_and_b32_e32 v197, 0xffff0000, v124
	v_cndmask_b32_e32 v204, 0, v179, vcc
	v_cmp_lt_u32_e32 vcc, 14, v209
	v_lshlrev_b32_e32 v190, 16, v121
	v_and_b32_e32 v191, 0xffff0000, v121
	v_lshlrev_b32_e32 v198, 16, v125
	v_and_b32_e32 v199, 0xffff0000, v125
	v_lshlrev_b32_e32 v192, 16, v122
	v_and_b32_e32 v193, 0xffff0000, v122
	v_lshlrev_b32_e32 v200, 16, v126
	v_and_b32_e32 v201, 0xffff0000, v126
	v_lshlrev_b32_e32 v194, 16, v123
	v_and_b32_e32 v195, 0xffff0000, v123
	v_lshlrev_b32_e32 v202, 16, v127
	v_and_b32_e32 v203, 0xffff0000, v127
	v_cndmask_b32_e32 v206, 0, v179, vcc
	v_pk_fma_f32 v[136:137], v[188:189], v[204:205], v[136:137] op_sel_hi:[1,0,1]
	v_pk_fma_f32 v[138:139], v[190:191], v[204:205], v[138:139] op_sel_hi:[1,0,1]
	v_pk_fma_f32 v[140:141], v[192:193], v[204:205], v[140:141] op_sel_hi:[1,0,1]
	v_pk_fma_f32 v[142:143], v[194:195], v[204:205], v[142:143] op_sel_hi:[1,0,1]
	v_pk_fma_f32 v[144:145], v[196:197], v[204:205], v[144:145] op_sel_hi:[1,0,1]
	v_pk_fma_f32 v[146:147], v[198:199], v[204:205], v[146:147] op_sel_hi:[1,0,1]
	v_pk_fma_f32 v[148:149], v[200:201], v[204:205], v[148:149] op_sel_hi:[1,0,1]
	v_pk_fma_f32 v[150:151], v[202:203], v[204:205], v[150:151] op_sel_hi:[1,0,1]
	v_pk_fma_f32 v[152:153], v[188:189], v[206:207], v[152:153] op_sel_hi:[1,0,1]
	v_pk_fma_f32 v[154:155], v[190:191], v[206:207], v[154:155] op_sel_hi:[1,0,1]
	v_pk_fma_f32 v[156:157], v[192:193], v[206:207], v[156:157] op_sel_hi:[1,0,1]
	v_pk_fma_f32 v[158:159], v[194:195], v[206:207], v[158:159] op_sel_hi:[1,0,1]
	v_pk_fma_f32 v[160:161], v[196:197], v[206:207], v[160:161] op_sel_hi:[1,0,1]
	v_pk_fma_f32 v[162:163], v[198:199], v[206:207], v[162:163] op_sel_hi:[1,0,1]
	v_pk_fma_f32 v[164:165], v[200:201], v[206:207], v[164:165] op_sel_hi:[1,0,1]
	v_pk_fma_f32 v[166:167], v[202:203], v[206:207], v[166:167] op_sel_hi:[1,0,1]
	s_waitcnt vmcnt(0)
	v_lshlrev_b32_e32 v188, 16, v128
	v_and_b32_e32 v189, 0xffff0000, v128
	v_lshlrev_b32_e32 v196, 16, v132
	v_and_b32_e32 v197, 0xffff0000, v132
	v_cmp_lt_u32_e32 vcc, 15, v209
	v_lshlrev_b32_e32 v190, 16, v129
	v_and_b32_e32 v191, 0xffff0000, v129
	v_lshlrev_b32_e32 v198, 16, v133
	v_and_b32_e32 v199, 0xffff0000, v133
	v_lshlrev_b32_e32 v192, 16, v130
	v_and_b32_e32 v193, 0xffff0000, v130
	v_lshlrev_b32_e32 v200, 16, v134
	v_and_b32_e32 v201, 0xffff0000, v134
	v_lshlrev_b32_e32 v194, 16, v131
	v_and_b32_e32 v195, 0xffff0000, v131
	v_lshlrev_b32_e32 v202, 16, v135
	v_and_b32_e32 v203, 0xffff0000, v135
	v_cndmask_b32_e32 v206, 0, v179, vcc
	v_pk_fma_f32 v[152:153], v[188:189], v[206:207], v[152:153] op_sel_hi:[1,0,1]
	v_pk_fma_f32 v[154:155], v[190:191], v[206:207], v[154:155] op_sel_hi:[1,0,1]
	v_pk_fma_f32 v[156:157], v[192:193], v[206:207], v[156:157] op_sel_hi:[1,0,1]
	v_pk_fma_f32 v[158:159], v[194:195], v[206:207], v[158:159] op_sel_hi:[1,0,1]
	v_pk_fma_f32 v[160:161], v[196:197], v[206:207], v[160:161] op_sel_hi:[1,0,1]
	v_pk_fma_f32 v[162:163], v[198:199], v[206:207], v[162:163] op_sel_hi:[1,0,1]
	v_pk_fma_f32 v[164:165], v[200:201], v[206:207], v[164:165] op_sel_hi:[1,0,1]
	v_pk_fma_f32 v[166:167], v[202:203], v[206:207], v[166:167] op_sel_hi:[1,0,1]
	v_cvt_f32_ubyte0_e32 v216, v208
	v_div_scale_f32 v217, s[2:3], v216, v216, 1.0
	v_rcp_f32_e32 v218, v217
	v_lshlrev_b32_e32 v188, 16, v0
	v_and_b32_e32 v189, 0xffff0000, v0
	v_lshlrev_b32_e32 v196, 16, v4
	v_and_b32_e32 v197, 0xffff0000, v4
	v_lshlrev_b32_e32 v190, 16, v1
	v_and_b32_e32 v191, 0xffff0000, v1
	v_lshlrev_b32_e32 v198, 16, v5
	v_and_b32_e32 v199, 0xffff0000, v5
	v_fma_f32 v219, -v217, v218, 1.0
	v_fmac_f32_e32 v218, v219, v218
	v_div_scale_f32 v220, vcc, 1.0, v216, 1.0
	v_mul_f32_e32 v221, v220, v218
	v_fma_f32 v222, -v217, v221, v220
	v_fmac_f32_e32 v221, v222, v218
	v_fma_f32 v217, -v217, v221, v220
	v_lshlrev_b32_e32 v192, 16, v2
	v_and_b32_e32 v193, 0xffff0000, v2
	v_div_fmas_f32 v217, v217, v218, v221
	v_div_fixup_f32 v216, v217, v216, 1.0
	v_lshlrev_b32_e32 v200, 16, v6
	v_and_b32_e32 v201, 0xffff0000, v6
	v_lshlrev_b32_e32 v194, 16, v3
	v_and_b32_e32 v195, 0xffff0000, v3
	v_lshlrev_b32_e32 v202, 16, v7
	v_and_b32_e32 v203, 0xffff0000, v7
	v_pk_fma_f32 v[136:137], v[216:217], v[136:137], v[188:189] op_sel_hi:[0,1,1] neg_lo:[0,0,1] neg_hi:[0,0,1]
	v_pk_fma_f32 v[138:139], v[216:217], v[138:139], v[190:191] op_sel_hi:[0,1,1] neg_lo:[0,0,1] neg_hi:[0,0,1]
	v_pk_fma_f32 v[140:141], v[216:217], v[140:141], v[192:193] op_sel_hi:[0,1,1] neg_lo:[0,0,1] neg_hi:[0,0,1]
	v_pk_fma_f32 v[142:143], v[216:217], v[142:143], v[194:195] op_sel_hi:[0,1,1] neg_lo:[0,0,1] neg_hi:[0,0,1]
	v_pk_fma_f32 v[144:145], v[216:217], v[144:145], v[196:197] op_sel_hi:[0,1,1] neg_lo:[0,0,1] neg_hi:[0,0,1]
	v_pk_fma_f32 v[146:147], v[216:217], v[146:147], v[198:199] op_sel_hi:[0,1,1] neg_lo:[0,0,1] neg_hi:[0,0,1]
	v_pk_fma_f32 v[148:149], v[216:217], v[148:149], v[200:201] op_sel_hi:[0,1,1] neg_lo:[0,0,1] neg_hi:[0,0,1]
	v_pk_fma_f32 v[150:151], v[216:217], v[150:151], v[202:203] op_sel_hi:[0,1,1] neg_lo:[0,0,1] neg_hi:[0,0,1]
	v_cvt_pk_bf16_f32 v136, v136, v137
	v_cvt_pk_bf16_f32 v137, v138, v139
	v_cvt_pk_bf16_f32 v138, v140, v141
	v_cvt_pk_bf16_f32 v139, v142, v143
	v_cvt_pk_bf16_f32 v140, v144, v145
	v_cvt_pk_bf16_f32 v141, v146, v147
	v_cvt_pk_bf16_f32 v142, v148, v149
	v_cvt_pk_bf16_f32 v143, v150, v151
	global_store_dwordx4 v211, v[136:139], s[50:51] offset:2048
	global_store_dwordx4 v211, v[140:143], s[50:51] offset:2064
	v_cvt_f32_ubyte0_e32 v216, v209
	v_div_scale_f32 v217, s[2:3], v216, v216, 1.0
	v_rcp_f32_e32 v218, v217
	v_lshlrev_b32_e32 v188, 16, v8
	v_and_b32_e32 v189, 0xffff0000, v8
	v_lshlrev_b32_e32 v196, 16, v12
	v_and_b32_e32 v197, 0xffff0000, v12
	v_lshlrev_b32_e32 v190, 16, v9
	v_and_b32_e32 v191, 0xffff0000, v9
	v_lshlrev_b32_e32 v198, 16, v13
	v_and_b32_e32 v199, 0xffff0000, v13
	v_fma_f32 v219, -v217, v218, 1.0
	v_fmac_f32_e32 v218, v219, v218
	v_div_scale_f32 v220, vcc, 1.0, v216, 1.0
	v_mul_f32_e32 v221, v220, v218
	v_fma_f32 v222, -v217, v221, v220
	v_fmac_f32_e32 v221, v222, v218
	v_fma_f32 v217, -v217, v221, v220
	v_lshlrev_b32_e32 v192, 16, v10
	v_and_b32_e32 v193, 0xffff0000, v10
	v_div_fmas_f32 v217, v217, v218, v221
	v_div_fixup_f32 v216, v217, v216, 1.0
	v_lshlrev_b32_e32 v200, 16, v14
	v_and_b32_e32 v201, 0xffff0000, v14
	v_lshlrev_b32_e32 v194, 16, v11
	v_and_b32_e32 v195, 0xffff0000, v11
	v_lshlrev_b32_e32 v202, 16, v15
	v_and_b32_e32 v203, 0xffff0000, v15
	v_pk_fma_f32 v[152:153], v[216:217], v[152:153], v[188:189] op_sel_hi:[0,1,1] neg_lo:[0,0,1] neg_hi:[0,0,1]
	v_pk_fma_f32 v[154:155], v[216:217], v[154:155], v[190:191] op_sel_hi:[0,1,1] neg_lo:[0,0,1] neg_hi:[0,0,1]
	v_pk_fma_f32 v[156:157], v[216:217], v[156:157], v[192:193] op_sel_hi:[0,1,1] neg_lo:[0,0,1] neg_hi:[0,0,1]
	v_pk_fma_f32 v[158:159], v[216:217], v[158:159], v[194:195] op_sel_hi:[0,1,1] neg_lo:[0,0,1] neg_hi:[0,0,1]
	v_pk_fma_f32 v[160:161], v[216:217], v[160:161], v[196:197] op_sel_hi:[0,1,1] neg_lo:[0,0,1] neg_hi:[0,0,1]
	v_pk_fma_f32 v[162:163], v[216:217], v[162:163], v[198:199] op_sel_hi:[0,1,1] neg_lo:[0,0,1] neg_hi:[0,0,1]
	v_pk_fma_f32 v[164:165], v[216:217], v[164:165], v[200:201] op_sel_hi:[0,1,1] neg_lo:[0,0,1] neg_hi:[0,0,1]
	v_pk_fma_f32 v[166:167], v[216:217], v[166:167], v[202:203] op_sel_hi:[0,1,1] neg_lo:[0,0,1] neg_hi:[0,0,1]
	v_cvt_pk_bf16_f32 v152, v152, v153
	v_cvt_pk_bf16_f32 v153, v154, v155
	v_cvt_pk_bf16_f32 v154, v156, v157
	v_cvt_pk_bf16_f32 v155, v158, v159
	v_cvt_pk_bf16_f32 v156, v160, v161
	v_cvt_pk_bf16_f32 v157, v162, v163
	v_cvt_pk_bf16_f32 v158, v164, v165
	v_cvt_pk_bf16_f32 v159, v166, v167
	global_store_dwordx4 v211, v[152:155], s[50:51] offset:0
	global_store_dwordx4 v211, v[156:159], s[50:51] offset:16
	s_add_i32 s1, s1, 1
	s_cmp_lt_u32 s1, 4
	s_cbranch_scc1 .Lpool_it
